# attention output (Y) stores of all three mixers made write-through
# baseline (speedup 1.0000x reference)
; __device__ __forceinline__ float half_sum(float m) { auto rr = __builtin_amdgcn_permlane32_swap(__float_as_uint(m), __float_as_uint(m), false, false); return __uint_as_float(rr[0]) + __uint_as_float(rr[1]); }
; __device__ __forceinline__ int lane_now() { int l; asm volatile("v_mbcnt_lo_u32_b32 %0, -1, 0\n\tv_mbcnt_hi_u32_b32 %0, -1, %0" : "=v"(l)); return l; }
; template <bool FIXM> __device__ __forceinline__ void diff_unit(int b, int h, int qb, float lam, const bf16* U, const bf16* VTa, bf16* Y, const float* subg, const float* qgain, const int* pos, unsigned char* lds, int tid, int wid, int lane) {
;     ...
;     float ss = 0.f;
; #pragma unroll
;     for (int db = 0; db < 4; ++db)
; #pragma unroll
;         for (int r = 0; r < 16; ++r) ss += o[db][r] * o[db][r];
;     ss = half_sum(ss);
;     const float rstd = 0.8f / sqrtf(ss * (1.f / 128.f) + EPS);
;     const int lane_e = lane_now();
;     const int hi_e = lane_e >> 5, tq_e = t0 + (lane_e & 31);
;     const bf16* gar = U + (rowbase + tq_e) * EU + C_GA + h * 128;
;     bf16* yr = Y + (rowbase + tq_e) * D + h * 128; u32x2 wprev = {0u, 0u};
; #pragma unroll
;     for (int db = 0; db < 4; ++db)
; #pragma unroll
;         for (int g4 = 0; g4 < 4; ++g4) {
;             const int e = 32 * db + 8 * g4 + 4 * hi_e;
;             const u32x2 gw = *(const u32x2*)(gar + e); const f32x4 sg = *(const f32x4*)(subg + e);
.LBB0_377:
	v_mul_f32_e32 v0, v115, v115
	v_fmac_f32_e32 v0, v114, v114
	v_fmac_f32_e32 v0, v116, v116
	v_fmac_f32_e32 v0, v117, v117
	v_fmac_f32_e32 v0, v118, v118
	v_fmac_f32_e32 v0, v119, v119
	v_fmac_f32_e32 v0, v120, v120
	v_fmac_f32_e32 v0, v121, v121
	v_fmac_f32_e32 v0, v122, v122
	v_fmac_f32_e32 v0, v123, v123
	v_fmac_f32_e32 v0, v124, v124
	v_fmac_f32_e32 v0, v125, v125
	v_fmac_f32_e32 v0, v126, v126
	v_fmac_f32_e32 v0, v127, v127
	v_fmac_f32_e32 v0, v128, v128
	v_fmac_f32_e32 v0, v129, v129
	v_fmac_f32_e32 v0, v34, v34
	v_fmac_f32_e32 v0, v35, v35
	v_fmac_f32_e32 v0, v36, v36
	v_fmac_f32_e32 v0, v37, v37
	v_fmac_f32_e32 v0, v38, v38
	v_fmac_f32_e32 v0, v39, v39
	v_fmac_f32_e32 v0, v40, v40
	v_fmac_f32_e32 v0, v41, v41
	v_fmac_f32_e32 v0, v42, v42
	v_fmac_f32_e32 v0, v43, v43
	v_fmac_f32_e32 v0, v44, v44
	v_fmac_f32_e32 v0, v45, v45
	v_fmac_f32_e32 v0, v46, v46
	v_fmac_f32_e32 v0, v47, v47
	v_fmac_f32_e32 v0, v48, v48
	v_fmac_f32_e32 v0, v49, v49
	v_fmac_f32_e32 v0, v18, v18
	v_fmac_f32_e32 v0, v19, v19
	v_fmac_f32_e32 v0, v20, v20
	v_fmac_f32_e32 v0, v21, v21
	v_fmac_f32_e32 v0, v22, v22
	v_fmac_f32_e32 v0, v23, v23
	v_fmac_f32_e32 v0, v24, v24
	v_fmac_f32_e32 v0, v25, v25
	v_fmac_f32_e32 v0, v26, v26
	v_fmac_f32_e32 v0, v27, v27
	v_fmac_f32_e32 v0, v28, v28
	v_fmac_f32_e32 v0, v29, v29
	v_fmac_f32_e32 v0, v30, v30
	v_fmac_f32_e32 v0, v31, v31
	v_fmac_f32_e32 v0, v32, v32
	v_fmac_f32_e32 v0, v33, v33
	v_fmac_f32_e32 v0, v2, v2
	v_fmac_f32_e32 v0, v3, v3
	v_fmac_f32_e32 v0, v4, v4
	v_fmac_f32_e32 v0, v5, v5
	v_fmac_f32_e32 v0, v6, v6
	v_fmac_f32_e32 v0, v7, v7
	v_fmac_f32_e32 v0, v8, v8
	v_fmac_f32_e32 v0, v9, v9
	v_fmac_f32_e32 v0, v10, v10
	v_fmac_f32_e32 v0, v11, v11
	v_fmac_f32_e32 v0, v12, v12
	v_fmac_f32_e32 v0, v13, v13
	v_fmac_f32_e32 v0, v14, v14
	v_fmac_f32_e32 v0, v15, v15
	v_pk_mul_f32 v[50:51], v[16:17], v[16:17]
	s_mov_b32 s0, 0xf800000
	v_add_f32_e32 v0, v50, v0
	v_add_f32_e32 v0, v51, v0
	v_mov_b32_e32 v50, v0
	s_nop 1
	v_permlane32_swap_b32_e32 v0, v50
	v_add_f32_e32 v0, v0, v50
	v_fmamk_f32 v0, v0, 0x3c000000, v223
	v_cmp_gt_f32_e32 vcc, s0, v0
	v_mul_f32_e32 v50, 0x4f800000, v0
	s_mov_b32 s2, 0x3f4ccccd
	v_cndmask_b32_e32 v0, v0, v50, vcc
	v_sqrt_f32_e32 v50, v0
	v_readlane_b32 s22, v251, 44
	v_readlane_b32 s23, v251, 45
	s_movk_i32 s20, 0x1600
	v_add_u32_e32 v51, -1, v50
	v_fma_f32 v52, -v51, v50, v0
	v_cmp_ge_f32_e64 s[0:1], 0, v52
	v_add_u32_e32 v52, 1, v50
	v_readlane_b32 s24, v251, 46
	v_cndmask_b32_e64 v51, v50, v51, s[0:1]
	v_fma_f32 v50, -v52, v50, v0
	v_cmp_lt_f32_e64 s[0:1], 0, v50
	v_readlane_b32 s25, v251, 47
	v_readlane_b32 s4, v252, 37
	v_cndmask_b32_e64 v50, v51, v52, s[0:1]
	v_mul_f32_e32 v51, 0x37800000, v50
	v_cndmask_b32_e32 v50, v50, v51, vcc
	v_cmp_class_f32_e32 vcc, v0, v224
	v_readlane_b32 s14, v252, 47
	v_readlane_b32 s15, v252, 48
	v_cndmask_b32_e32 v0, v50, v0, vcc
	v_div_scale_f32 v50, s[0:1], v0, v0, s2
	v_rcp_f32_e32 v51, v50
	v_readlane_b32 s0, v251, 50
	v_readlane_b32 s76, v251, 32
	v_readlane_b32 s77, v251, 33
	v_fma_f32 v52, -v50, v51, 1.0
	v_fmac_f32_e32 v51, v52, v51
	v_div_scale_f32 v52, vcc, s2, v0, s2
	v_mul_f32_e32 v53, v52, v51
	v_fma_f32 v54, -v50, v53, v52
	v_fmac_f32_e32 v53, v54, v51
	v_fma_f32 v50, -v50, v53, v52
	v_div_fmas_f32 v50, v50, v51, v53
	v_div_fixup_f32 v58, v50, v0, s2
	v_mbcnt_lo_u32_b32 v0, -1, 0
	v_mbcnt_hi_u32_b32 v0, -1, v0
	v_pk_mul_f32 v[68:69], v[114:115], v[58:59] op_sel_hi:[1,0]
	v_ashrrev_i32_e32 v55, 5, v0
	v_and_or_b32 v0, v0, 31, s0
	v_readlane_b32 s0, v251, 42
	v_readlane_b32 s1, v251, 43
	v_lshl_add_u64 v[50:51], s[22:23], 0, v[0:1]
	v_lshlrev_b32_e32 v54, 2, v55
	v_mov_b64_e32 v[52:53], s[0:1]
	v_mad_u64_u32 v[52:53], s[0:1], v50, s20, v[52:53]
	v_mad_i32_i24 v53, v51, s20, v53
	v_lshlrev_b64 v[50:51], 11, v[50:51]
	v_lshlrev_b32_e32 v56, 3, v55
	v_ashrrev_i32_e32 v55, 31, v54
	v_lshl_add_u64 v[50:51], s[24:25], 0, v[50:51]
	v_ashrrev_i32_e32 v57, 31, v56
	v_lshl_add_u64 v[62:63], v[54:55], 1, v[52:53]
	v_lshl_add_u64 v[60:61], v[56:57], 1, v[50:51]
	global_load_dwordx2 v[56:57], v[62:63], off offset:2048
	v_lshl_add_u64 v[64:65], v[54:55], 2, s[14:15]
	global_load_dwordx4 v[50:53], v[64:65], off
	v_pk_mul_f32 v[70:71], v[120:121], v[58:59] op_sel_hi:[1,0]
	v_pk_mul_f32 v[34:35], v[34:35], v[58:59] op_sel_hi:[1,0]
	v_pk_mul_f32 v[36:37], v[36:37], v[58:59] op_sel_hi:[1,0]
	v_pk_mul_f32 v[40:41], v[40:41], v[58:59] op_sel_hi:[1,0]
	v_pk_mul_f32 v[38:39], v[38:39], v[58:59] op_sel_hi:[1,0]
	v_pk_mul_f32 v[42:43], v[42:43], v[58:59] op_sel_hi:[1,0]
	v_pk_mul_f32 v[48:49], v[48:49], v[58:59] op_sel_hi:[1,0]
	v_pk_mul_f32 v[18:19], v[18:19], v[58:59] op_sel_hi:[1,0]
	v_pk_mul_f32 v[20:21], v[20:21], v[58:59] op_sel_hi:[1,0]
	v_pk_mul_f32 v[24:25], v[24:25], v[58:59] op_sel_hi:[1,0]
	v_pk_mul_f32 v[22:23], v[22:23], v[58:59] op_sel_hi:[1,0]
	v_pk_mul_f32 v[26:27], v[26:27], v[58:59] op_sel_hi:[1,0]
	v_pk_mul_f32 v[32:33], v[32:33], v[58:59] op_sel_hi:[1,0]
	v_pk_mul_f32 v[2:3], v[2:3], v[58:59] op_sel_hi:[1,0]
	v_pk_mul_f32 v[4:5], v[4:5], v[58:59] op_sel_hi:[1,0]
	v_pk_mul_f32 v[8:9], v[8:9], v[58:59] op_sel_hi:[1,0]
	v_pk_mul_f32 v[6:7], v[6:7], v[58:59] op_sel_hi:[1,0]
	v_pk_mul_f32 v[10:11], v[10:11], v[58:59] op_sel_hi:[1,0]
	v_pk_mul_f32 v[16:17], v[16:17], v[58:59] op_sel_hi:[1,0]
	v_readlane_b32 s0, v251, 51
	v_readlane_b32 s1, v251, 52
	v_readlane_b32 s5, v252, 38
	v_readlane_b32 s6, v252, 39
	v_readlane_b32 s7, v252, 40
	v_readlane_b32 s8, v252, 41
	v_readlane_b32 s9, v252, 42
	v_readlane_b32 s10, v252, 43
	v_readlane_b32 s11, v252, 44
	v_readlane_b32 s12, v252, 45
	v_readlane_b32 s13, v252, 46
	v_readlane_b32 s16, v252, 49
	v_readlane_b32 s17, v252, 50
	v_readlane_b32 s18, v252, 51
	v_readlane_b32 s19, v252, 52
	s_waitcnt vmcnt(0)
; __device__ __forceinline__ unsigned cvtpk(float lo, float hi) { f32x2_t v = {lo, hi}; bf16x2_t b = __builtin_convertvector(v, bf16x2_t); return __builtin_bit_cast(unsigned, b); }
; __device__ __forceinline__ float bf_lo(unsigned w) { return __uint_as_float(w << 16); }
; __device__ __forceinline__ float bf_hi(unsigned w) { return __uint_as_float(w & 0xffff0000u); }
; __device__ __forceinline__ float silu_f(float x) { return x * __builtin_amdgcn_rcpf(1.f + __expf(-x)); }
; __device__ __forceinline__ void store_pair16(bf16* rowp16, u32x2 wk, u32x2 wk1) {
;     auto r0 = __builtin_amdgcn_permlane32_swap(wk.x, wk1.x, false, false);
;     auto r1 = __builtin_amdgcn_permlane32_swap(wk.y, wk1.y, false, false);
;     u32x4 v; v.x = r0[0]; v.y = r1[0]; v.z = r0[1]; v.w = r1[1];
;     *(u32x4*)rowp16 = v;
; }
; template <bool FIXM> __device__ __forceinline__ void diff_unit(int b, int h, int qb, float lam, const bf16* U, const bf16* VTa, bf16* Y, const float* subg, const float* qgain, const int* pos, unsigned char* lds, int tid, int wid, int lane) {
;     ...
; #pragma unroll
;     for (int db = 0; db < 4; ++db)
; #pragma unroll
;         for (int g4 = 0; g4 < 4; ++g4) {
;             const int e = 32 * db + 8 * g4 + 4 * hi_e;
;             const u32x2 gw = *(const u32x2*)(gar + e); const f32x4 sg = *(const f32x4*)(subg + e);
;             const float y0 = o[db][4 * g4 + 0] * rstd * sg.x * silu_f(bf_lo(gw.x)), y1 = o[db][4 * g4 + 1] * rstd * sg.y * silu_f(bf_hi(gw.x));
;             const float y2 = o[db][4 * g4 + 2] * rstd * sg.z * silu_f(bf_lo(gw.y)), y3 = o[db][4 * g4 + 3] * rstd * sg.w * silu_f(bf_hi(gw.y));
;             u32x2 w; w.x = cvtpk(y0, y1); w.y = cvtpk(y2, y3);
;             if ((g4 & 1) == 0) wprev = w; else store_pair16(yr + 32 * db + 16 * (g4 >> 1) + 8 * hi_e, wprev, w);
	v_lshlrev_b32_e32 v54, 16, v56
	v_mul_f32_e32 v0, 0xbfb8aa3b, v54
	v_exp_f32_e32 v0, v0
	v_and_b32_e32 v55, 0xffff0000, v56
	v_pk_mul_f32 v[50:51], v[50:51], v[68:69]
	v_add_f32_e32 v0, 1.0, v0
	v_rcp_f32_e32 v66, v0
	v_mul_f32_e32 v0, 0xbfb8aa3b, v55
	v_exp_f32_e32 v0, v0
	s_nop 0
	v_add_f32_e32 v0, 1.0, v0
	v_rcp_f32_e32 v67, v0
	s_nop 0
	v_pk_mul_f32 v[54:55], v[66:67], v[54:55]
	s_nop 0
	v_pk_mul_f32 v[50:51], v[50:51], v[54:55]
	v_lshlrev_b32_e32 v54, 16, v57
	v_mul_f32_e32 v0, 0xbfb8aa3b, v54
	v_exp_f32_e32 v0, v0
	v_and_b32_e32 v55, 0xffff0000, v57
	v_pk_mul_f32 v[66:67], v[116:117], v[58:59] op_sel_hi:[1,0]
	v_cvt_pk_bf16_f32 v50, v50, v51
	v_add_f32_e32 v0, 1.0, v0
	v_rcp_f32_e32 v56, v0
	v_mul_f32_e32 v0, 0xbfb8aa3b, v55
	v_exp_f32_e32 v0, v0
	v_pk_mul_f32 v[52:53], v[52:53], v[66:67]
	v_add_f32_e32 v0, 1.0, v0
	v_rcp_f32_e32 v57, v0
	s_nop 0
	v_pk_mul_f32 v[54:55], v[56:57], v[54:55]
	s_nop 0
	v_pk_mul_f32 v[52:53], v[52:53], v[54:55]
	s_nop 0
	v_cvt_pk_bf16_f32 v51, v52, v53
	global_load_dwordx4 v[54:57], v[64:65], off offset:32
	global_load_dwordx2 v[52:53], v[62:63], off offset:2064
	s_waitcnt vmcnt(0)
	v_pk_mul_f32 v[56:57], v[56:57], v[70:71]
	v_lshlrev_b32_e32 v66, 16, v53
	v_mul_f32_e32 v0, 0xbfb8aa3b, v66
	v_exp_f32_e32 v0, v0
	v_and_b32_e32 v67, 0xffff0000, v53
	v_pk_mul_f32 v[70:71], v[128:129], v[58:59] op_sel_hi:[1,0]
	v_add_f32_e32 v0, 1.0, v0
	v_rcp_f32_e32 v68, v0
	v_mul_f32_e32 v0, 0xbfb8aa3b, v67
	v_exp_f32_e32 v0, v0
	s_nop 0
	v_add_f32_e32 v0, 1.0, v0
	v_rcp_f32_e32 v69, v0
	s_nop 0
	v_pk_mul_f32 v[66:67], v[68:69], v[66:67]
	s_nop 0
	v_pk_mul_f32 v[56:57], v[56:57], v[66:67]
	v_pk_mul_f32 v[68:69], v[118:119], v[58:59] op_sel_hi:[1,0]
	v_cvt_pk_bf16_f32 v53, v56, v57
	v_lshlrev_b32_e32 v56, 16, v52
	v_mul_f32_e32 v0, 0xbfb8aa3b, v56
	v_exp_f32_e32 v0, v0
	v_and_b32_e32 v57, 0xffff0000, v52
	v_pk_mul_f32 v[54:55], v[54:55], v[68:69]
	v_permlane32_swap_b32_e32 v51, v53
	v_add_f32_e32 v0, 1.0, v0
	v_rcp_f32_e32 v66, v0
	v_mul_f32_e32 v0, 0xbfb8aa3b, v57
	v_exp_f32_e32 v0, v0
	v_pk_mul_f32 v[68:69], v[122:123], v[58:59] op_sel_hi:[1,0]
	v_add_f32_e32 v0, 1.0, v0
	v_rcp_f32_e32 v67, v0
	s_nop 0
	v_pk_mul_f32 v[56:57], v[66:67], v[56:57]
	s_nop 0
	v_pk_mul_f32 v[54:55], v[54:55], v[56:57]
	s_nop 0
	v_cvt_pk_bf16_f32 v52, v54, v55
	s_nop 1
	v_permlane32_swap_b32_e32 v50, v52
	global_store_dwordx4 v[60:61], v[50:53], off sc1
	global_load_dwordx2 v[54:55], v[62:63], off offset:2080
	s_nop 0
	global_load_dwordx4 v[50:53], v[64:65], off offset:64
	s_waitcnt vmcnt(0)
	v_lshlrev_b32_e32 v56, 16, v54
	v_mul_f32_e32 v0, 0xbfb8aa3b, v56
	v_exp_f32_e32 v0, v0
	v_and_b32_e32 v57, 0xffff0000, v54
	v_lshlrev_b32_e32 v54, 16, v55
	v_pk_mul_f32 v[50:51], v[68:69], v[50:51]
	v_add_f32_e32 v0, 1.0, v0
	v_rcp_f32_e32 v66, v0
	v_mul_f32_e32 v0, 0xbfb8aa3b, v57
	v_exp_f32_e32 v0, v0
	v_and_b32_e32 v55, 0xffff0000, v55
	v_add_f32_e32 v0, 1.0, v0
	v_rcp_f32_e32 v67, v0
	v_mul_f32_e32 v0, 0xbfb8aa3b, v54
	v_exp_f32_e32 v0, v0
	v_pk_mul_f32 v[56:57], v[66:67], v[56:57]
	s_nop 0
	v_pk_mul_f32 v[50:51], v[50:51], v[56:57]
	v_add_f32_e32 v0, 1.0, v0
	v_rcp_f32_e32 v56, v0
	v_mul_f32_e32 v0, 0xbfb8aa3b, v55
	v_exp_f32_e32 v0, v0
	v_pk_mul_f32 v[66:67], v[124:125], v[58:59] op_sel_hi:[1,0]
	v_cvt_pk_bf16_f32 v50, v50, v51
	v_pk_mul_f32 v[52:53], v[66:67], v[52:53]
	v_add_f32_e32 v0, 1.0, v0
	v_rcp_f32_e32 v57, v0
	s_nop 0
	v_pk_mul_f32 v[54:55], v[56:57], v[54:55]
	s_nop 0
	v_pk_mul_f32 v[52:53], v[52:53], v[54:55]
	s_nop 0
	v_cvt_pk_bf16_f32 v51, v52, v53
	global_load_dwordx4 v[54:57], v[64:65], off offset:96
	global_load_dwordx2 v[52:53], v[62:63], off offset:2096
	s_waitcnt vmcnt(0)
	v_pk_mul_f32 v[56:57], v[70:71], v[56:57]
	v_lshlrev_b32_e32 v66, 16, v53
	v_mul_f32_e32 v0, 0xbfb8aa3b, v66
	v_exp_f32_e32 v0, v0
	v_and_b32_e32 v67, 0xffff0000, v53
	v_add_f32_e32 v0, 1.0, v0
	v_rcp_f32_e32 v68, v0
	v_mul_f32_e32 v0, 0xbfb8aa3b, v67
	v_exp_f32_e32 v0, v0
	s_nop 0
	v_add_f32_e32 v0, 1.0, v0
	v_rcp_f32_e32 v69, v0
	s_nop 0
	v_pk_mul_f32 v[66:67], v[68:69], v[66:67]
	s_nop 0
	v_pk_mul_f32 v[56:57], v[56:57], v[66:67]
	v_pk_mul_f32 v[68:69], v[126:127], v[58:59] op_sel_hi:[1,0]
	v_cvt_pk_bf16_f32 v53, v56, v57
	v_lshlrev_b32_e32 v56, 16, v52
	v_mul_f32_e32 v0, 0xbfb8aa3b, v56
	v_exp_f32_e32 v0, v0
	v_and_b32_e32 v57, 0xffff0000, v52
	v_pk_mul_f32 v[54:55], v[68:69], v[54:55]
	v_permlane32_swap_b32_e32 v51, v53
	v_add_f32_e32 v0, 1.0, v0
	v_rcp_f32_e32 v66, v0
	v_mul_f32_e32 v0, 0xbfb8aa3b, v57
	v_exp_f32_e32 v0, v0
	s_nop 0
	v_add_f32_e32 v0, 1.0, v0
	v_rcp_f32_e32 v67, v0
	s_nop 0
	v_pk_mul_f32 v[56:57], v[66:67], v[56:57]
	s_nop 0
	v_pk_mul_f32 v[54:55], v[54:55], v[56:57]
	s_nop 0
	v_cvt_pk_bf16_f32 v52, v54, v55
	s_nop 1
	v_permlane32_swap_b32_e32 v50, v52
	global_store_dwordx4 v[60:61], v[50:53], off offset:32 sc1
	global_load_dwordx2 v[54:55], v[62:63], off offset:2112
	s_nop 0
	global_load_dwordx4 v[50:53], v[64:65], off offset:128
	s_waitcnt vmcnt(0)
	v_lshlrev_b32_e32 v56, 16, v54
	v_mul_f32_e32 v0, 0xbfb8aa3b, v56
	v_exp_f32_e32 v0, v0
	v_and_b32_e32 v57, 0xffff0000, v54
	v_pk_mul_f32 v[34:35], v[34:35], v[50:51]
	v_pk_mul_f32 v[36:37], v[36:37], v[52:53]
	v_add_f32_e32 v0, 1.0, v0
	v_rcp_f32_e32 v66, v0
	v_mul_f32_e32 v0, 0xbfb8aa3b, v57
	v_exp_f32_e32 v0, v0
	s_nop 0
	v_add_f32_e32 v0, 1.0, v0
	v_rcp_f32_e32 v67, v0
	s_nop 0
	v_pk_mul_f32 v[50:51], v[66:67], v[56:57]
	s_nop 0
	v_pk_mul_f32 v[34:35], v[34:35], v[50:51]
	v_lshlrev_b32_e32 v50, 16, v55
	v_mul_f32_e32 v0, 0xbfb8aa3b, v50
	v_exp_f32_e32 v0, v0
	v_and_b32_e32 v51, 0xffff0000, v55
	v_cvt_pk_bf16_f32 v34, v34, v35
	v_add_f32_e32 v0, 1.0, v0
	v_rcp_f32_e32 v54, v0
	v_mul_f32_e32 v0, 0xbfb8aa3b, v51
	v_exp_f32_e32 v0, v0
	s_nop 0
	v_add_f32_e32 v0, 1.0, v0
	v_rcp_f32_e32 v55, v0
	s_nop 0
	v_pk_mul_f32 v[50:51], v[54:55], v[50:51]
	s_nop 0
	v_pk_mul_f32 v[36:37], v[36:37], v[50:51]
	s_nop 0
	v_cvt_pk_bf16_f32 v35, v36, v37
	global_load_dwordx4 v[50:53], v[64:65], off offset:160
	global_load_dwordx2 v[36:37], v[62:63], off offset:2128
	s_waitcnt vmcnt(0)
; __device__ __forceinline__ unsigned cvtpk(float lo, float hi) { f32x2_t v = {lo, hi}; bf16x2_t b = __builtin_convertvector(v, bf16x2_t); return __builtin_bit_cast(unsigned, b); }
; __device__ __forceinline__ float bf_lo(unsigned w) { return __uint_as_float(w << 16); }
; __device__ __forceinline__ float bf_hi(unsigned w) { return __uint_as_float(w & 0xffff0000u); }
; __device__ __forceinline__ float silu_f(float x) { return x * __builtin_amdgcn_rcpf(1.f + __expf(-x)); }
; __device__ __forceinline__ void store_pair16(bf16* rowp16, u32x2 wk, u32x2 wk1) {
;     auto r0 = __builtin_amdgcn_permlane32_swap(wk.x, wk1.x, false, false);
;     auto r1 = __builtin_amdgcn_permlane32_swap(wk.y, wk1.y, false, false);
;     u32x4 v; v.x = r0[0]; v.y = r1[0]; v.z = r0[1]; v.w = r1[1];
;     *(u32x4*)rowp16 = v;
; }
; template <bool FIXM> __device__ __forceinline__ void diff_unit(int b, int h, int qb, float lam, const bf16* U, const bf16* VTa, bf16* Y, const float* subg, const float* qgain, const int* pos, unsigned char* lds, int tid, int wid, int lane) {
;     ...
; #pragma unroll
;     for (int db = 0; db < 4; ++db)
; #pragma unroll
;         for (int g4 = 0; g4 < 4; ++g4) {
;             const int e = 32 * db + 8 * g4 + 4 * hi_e;
;             const u32x2 gw = *(const u32x2*)(gar + e); const f32x4 sg = *(const f32x4*)(subg + e);
;             const float y0 = o[db][4 * g4 + 0] * rstd * sg.x * silu_f(bf_lo(gw.x)), y1 = o[db][4 * g4 + 1] * rstd * sg.y * silu_f(bf_hi(gw.x));
;             const float y2 = o[db][4 * g4 + 2] * rstd * sg.z * silu_f(bf_lo(gw.y)), y3 = o[db][4 * g4 + 3] * rstd * sg.w * silu_f(bf_hi(gw.y));
;             u32x2 w; w.x = cvtpk(y0, y1); w.y = cvtpk(y2, y3);
;             if ((g4 & 1) == 0) wprev = w; else store_pair16(yr + 32 * db + 16 * (g4 >> 1) + 8 * hi_e, wprev, w);
	v_pk_mul_f32 v[40:41], v[40:41], v[52:53]
	v_lshlrev_b32_e32 v54, 16, v37
	v_mul_f32_e32 v0, 0xbfb8aa3b, v54
	v_exp_f32_e32 v0, v0
	v_and_b32_e32 v55, 0xffff0000, v37
	v_pk_mul_f32 v[38:39], v[38:39], v[50:51]
	v_add_f32_e32 v0, 1.0, v0
	v_rcp_f32_e32 v56, v0
	v_mul_f32_e32 v0, 0xbfb8aa3b, v55
	v_exp_f32_e32 v0, v0
	s_nop 0
	v_add_f32_e32 v0, 1.0, v0
	v_rcp_f32_e32 v57, v0
	s_nop 0
	v_pk_mul_f32 v[52:53], v[56:57], v[54:55]
	s_nop 0
	v_pk_mul_f32 v[40:41], v[40:41], v[52:53]
	s_nop 0
	v_cvt_pk_bf16_f32 v37, v40, v41
	v_lshlrev_b32_e32 v40, 16, v36
	v_mul_f32_e32 v0, 0xbfb8aa3b, v40
	v_exp_f32_e32 v0, v0
	v_and_b32_e32 v41, 0xffff0000, v36
	v_permlane32_swap_b32_e32 v35, v37
	v_add_f32_e32 v0, 1.0, v0
	v_rcp_f32_e32 v52, v0
	v_mul_f32_e32 v0, 0xbfb8aa3b, v41
	v_exp_f32_e32 v0, v0
	s_nop 0
	v_add_f32_e32 v0, 1.0, v0
	v_rcp_f32_e32 v53, v0
	s_nop 0
	v_pk_mul_f32 v[40:41], v[52:53], v[40:41]
	s_nop 0
	v_pk_mul_f32 v[38:39], v[38:39], v[40:41]
	s_nop 0
	v_cvt_pk_bf16_f32 v36, v38, v39
	s_nop 1
	v_permlane32_swap_b32_e32 v34, v36
	global_store_dwordx4 v[60:61], v[34:37], off offset:64 sc1
	global_load_dwordx2 v[38:39], v[62:63], off offset:2144
	s_nop 0
	global_load_dwordx4 v[34:37], v[64:65], off offset:192
	s_waitcnt vmcnt(0)
	v_lshlrev_b32_e32 v40, 16, v38
	v_mul_f32_e32 v0, 0xbfb8aa3b, v40
	v_exp_f32_e32 v0, v0
	v_and_b32_e32 v41, 0xffff0000, v38
	v_lshlrev_b32_e32 v38, 16, v39
	v_pk_mul_f32 v[34:35], v[42:43], v[34:35]
	v_add_f32_e32 v0, 1.0, v0
	v_rcp_f32_e32 v50, v0
	v_mul_f32_e32 v0, 0xbfb8aa3b, v41
	v_exp_f32_e32 v0, v0
	v_and_b32_e32 v39, 0xffff0000, v39
	v_pk_mul_f32 v[42:43], v[44:45], v[58:59] op_sel_hi:[1,0]
	v_add_f32_e32 v0, 1.0, v0
	v_rcp_f32_e32 v51, v0
	v_mul_f32_e32 v0, 0xbfb8aa3b, v38
	v_exp_f32_e32 v0, v0
	v_pk_mul_f32 v[36:37], v[42:43], v[36:37]
	v_pk_mul_f32 v[40:41], v[50:51], v[40:41]
	v_add_f32_e32 v0, 1.0, v0
	v_pk_mul_f32 v[34:35], v[34:35], v[40:41]
	v_rcp_f32_e32 v40, v0
	v_mul_f32_e32 v0, 0xbfb8aa3b, v39
	v_exp_f32_e32 v0, v0
	v_cvt_pk_bf16_f32 v34, v34, v35
	v_add_f32_e32 v0, 1.0, v0
	v_rcp_f32_e32 v41, v0
	s_nop 0
	v_pk_mul_f32 v[38:39], v[40:41], v[38:39]
	s_nop 0
	v_pk_mul_f32 v[36:37], v[36:37], v[38:39]
	s_nop 0
	v_cvt_pk_bf16_f32 v35, v36, v37
	global_load_dwordx4 v[38:41], v[64:65], off offset:224
	global_load_dwordx2 v[36:37], v[62:63], off offset:2160
	s_waitcnt vmcnt(0)
	v_pk_mul_f32 v[40:41], v[48:49], v[40:41]
	v_lshlrev_b32_e32 v42, 16, v37
	v_mul_f32_e32 v0, 0xbfb8aa3b, v42
	v_exp_f32_e32 v0, v0
	v_and_b32_e32 v43, 0xffff0000, v37
	v_add_f32_e32 v0, 1.0, v0
	v_rcp_f32_e32 v44, v0
	v_mul_f32_e32 v0, 0xbfb8aa3b, v43
	v_exp_f32_e32 v0, v0
	s_nop 0
	v_add_f32_e32 v0, 1.0, v0
	v_rcp_f32_e32 v45, v0
	s_nop 0
	v_pk_mul_f32 v[42:43], v[44:45], v[42:43]
	s_nop 0
	v_pk_mul_f32 v[40:41], v[40:41], v[42:43]
	v_pk_mul_f32 v[44:45], v[46:47], v[58:59] op_sel_hi:[1,0]
	v_cvt_pk_bf16_f32 v37, v40, v41
	v_lshlrev_b32_e32 v40, 16, v36
	v_mul_f32_e32 v0, 0xbfb8aa3b, v40
	v_exp_f32_e32 v0, v0
	v_and_b32_e32 v41, 0xffff0000, v36
	v_pk_mul_f32 v[38:39], v[44:45], v[38:39]
	v_permlane32_swap_b32_e32 v35, v37
	v_add_f32_e32 v0, 1.0, v0
	v_rcp_f32_e32 v42, v0
	v_mul_f32_e32 v0, 0xbfb8aa3b, v41
	v_exp_f32_e32 v0, v0
	s_nop 0
	v_add_f32_e32 v0, 1.0, v0
	v_rcp_f32_e32 v43, v0
	s_nop 0
	v_pk_mul_f32 v[40:41], v[42:43], v[40:41]
	s_nop 0
	v_pk_mul_f32 v[38:39], v[38:39], v[40:41]
	s_nop 0
	v_cvt_pk_bf16_f32 v36, v38, v39
	s_nop 1
	v_permlane32_swap_b32_e32 v34, v36
	global_store_dwordx4 v[60:61], v[34:37], off offset:96 sc1
	global_load_dwordx2 v[38:39], v[62:63], off offset:2176
	s_nop 0
	global_load_dwordx4 v[34:37], v[64:65], off offset:256
	s_waitcnt vmcnt(0)
	v_lshlrev_b32_e32 v40, 16, v38
	v_mul_f32_e32 v0, 0xbfb8aa3b, v40
	v_exp_f32_e32 v0, v0
	v_and_b32_e32 v41, 0xffff0000, v38
	v_pk_mul_f32 v[18:19], v[18:19], v[34:35]
	v_pk_mul_f32 v[20:21], v[20:21], v[36:37]
	v_add_f32_e32 v0, 1.0, v0
	v_rcp_f32_e32 v42, v0
	v_mul_f32_e32 v0, 0xbfb8aa3b, v41
	v_exp_f32_e32 v0, v0
	s_nop 0
	v_add_f32_e32 v0, 1.0, v0
	v_rcp_f32_e32 v43, v0
	s_nop 0
	v_pk_mul_f32 v[34:35], v[42:43], v[40:41]
	s_nop 0
	v_pk_mul_f32 v[18:19], v[18:19], v[34:35]
	v_lshlrev_b32_e32 v34, 16, v39
	v_mul_f32_e32 v0, 0xbfb8aa3b, v34
	v_exp_f32_e32 v0, v0
	v_and_b32_e32 v35, 0xffff0000, v39
	v_cvt_pk_bf16_f32 v18, v18, v19
	v_add_f32_e32 v0, 1.0, v0
	v_rcp_f32_e32 v38, v0
	v_mul_f32_e32 v0, 0xbfb8aa3b, v35
	v_exp_f32_e32 v0, v0
	s_nop 0
	v_add_f32_e32 v0, 1.0, v0
	v_rcp_f32_e32 v39, v0
	s_nop 0
	v_pk_mul_f32 v[34:35], v[38:39], v[34:35]
	s_nop 0
	v_pk_mul_f32 v[20:21], v[20:21], v[34:35]
	s_nop 0
	v_cvt_pk_bf16_f32 v19, v20, v21
	global_load_dwordx4 v[34:37], v[64:65], off offset:288
	global_load_dwordx2 v[20:21], v[62:63], off offset:2192
	s_waitcnt vmcnt(0)
	v_pk_mul_f32 v[24:25], v[24:25], v[36:37]
	v_lshlrev_b32_e32 v38, 16, v21
	v_mul_f32_e32 v0, 0xbfb8aa3b, v38
	v_exp_f32_e32 v0, v0
	v_and_b32_e32 v39, 0xffff0000, v21
	v_pk_mul_f32 v[22:23], v[22:23], v[34:35]
	v_add_f32_e32 v0, 1.0, v0
	v_rcp_f32_e32 v40, v0
	v_mul_f32_e32 v0, 0xbfb8aa3b, v39
	v_exp_f32_e32 v0, v0
	s_nop 0
	v_add_f32_e32 v0, 1.0, v0
	v_rcp_f32_e32 v41, v0
	s_nop 0
	v_pk_mul_f32 v[36:37], v[40:41], v[38:39]
	s_nop 0
	v_pk_mul_f32 v[24:25], v[24:25], v[36:37]
	s_nop 0
	v_cvt_pk_bf16_f32 v21, v24, v25
	v_lshlrev_b32_e32 v24, 16, v20
	v_mul_f32_e32 v0, 0xbfb8aa3b, v24
	v_exp_f32_e32 v0, v0
	v_and_b32_e32 v25, 0xffff0000, v20
	v_permlane32_swap_b32_e32 v19, v21
	v_add_f32_e32 v0, 1.0, v0
	v_rcp_f32_e32 v36, v0
	v_mul_f32_e32 v0, 0xbfb8aa3b, v25
	v_exp_f32_e32 v0, v0
	s_nop 0
	v_add_f32_e32 v0, 1.0, v0
	v_rcp_f32_e32 v37, v0
	s_nop 0
	v_pk_mul_f32 v[24:25], v[36:37], v[24:25]
	s_nop 0
	v_pk_mul_f32 v[22:23], v[22:23], v[24:25]
	s_nop 0
	v_cvt_pk_bf16_f32 v20, v22, v23
	s_nop 1
	v_permlane32_swap_b32_e32 v18, v20
	global_store_dwordx4 v[60:61], v[18:21], off offset:128 sc1
	global_load_dwordx2 v[22:23], v[62:63], off offset:2208
	s_nop 0
	global_load_dwordx4 v[18:21], v[64:65], off offset:320
	s_waitcnt vmcnt(0)
; __device__ __forceinline__ unsigned cvtpk(float lo, float hi) { f32x2_t v = {lo, hi}; bf16x2_t b = __builtin_convertvector(v, bf16x2_t); return __builtin_bit_cast(unsigned, b); }
; __device__ __forceinline__ float bf_lo(unsigned w) { return __uint_as_float(w << 16); }
; __device__ __forceinline__ float bf_hi(unsigned w) { return __uint_as_float(w & 0xffff0000u); }
; __device__ __forceinline__ float silu_f(float x) { return x * __builtin_amdgcn_rcpf(1.f + __expf(-x)); }
; __device__ __forceinline__ void store_pair16(bf16* rowp16, u32x2 wk, u32x2 wk1) {
;     auto r0 = __builtin_amdgcn_permlane32_swap(wk.x, wk1.x, false, false);
;     auto r1 = __builtin_amdgcn_permlane32_swap(wk.y, wk1.y, false, false);
;     u32x4 v; v.x = r0[0]; v.y = r1[0]; v.z = r0[1]; v.w = r1[1];
;     *(u32x4*)rowp16 = v;
; }
; template <bool FIXM> __device__ __forceinline__ void diff_unit(int b, int h, int qb, float lam, const bf16* U, const bf16* VTa, bf16* Y, const float* subg, const float* qgain, const int* pos, unsigned char* lds, int tid, int wid, int lane) {
;     ...
; #pragma unroll
;     for (int db = 0; db < 4; ++db)
; #pragma unroll
;         for (int g4 = 0; g4 < 4; ++g4) {
;             const int e = 32 * db + 8 * g4 + 4 * hi_e;
;             const u32x2 gw = *(const u32x2*)(gar + e); const f32x4 sg = *(const f32x4*)(subg + e);
;             const float y0 = o[db][4 * g4 + 0] * rstd * sg.x * silu_f(bf_lo(gw.x)), y1 = o[db][4 * g4 + 1] * rstd * sg.y * silu_f(bf_hi(gw.x));
;             const float y2 = o[db][4 * g4 + 2] * rstd * sg.z * silu_f(bf_lo(gw.y)), y3 = o[db][4 * g4 + 3] * rstd * sg.w * silu_f(bf_hi(gw.y));
;             u32x2 w; w.x = cvtpk(y0, y1); w.y = cvtpk(y2, y3);
;             if ((g4 & 1) == 0) wprev = w; else store_pair16(yr + 32 * db + 16 * (g4 >> 1) + 8 * hi_e, wprev, w);
	v_lshlrev_b32_e32 v24, 16, v22
	v_mul_f32_e32 v0, 0xbfb8aa3b, v24
	v_exp_f32_e32 v0, v0
	v_and_b32_e32 v25, 0xffff0000, v22
	v_lshlrev_b32_e32 v22, 16, v23
	v_pk_mul_f32 v[18:19], v[26:27], v[18:19]
	v_add_f32_e32 v0, 1.0, v0
	v_rcp_f32_e32 v34, v0
	v_mul_f32_e32 v0, 0xbfb8aa3b, v25
	v_exp_f32_e32 v0, v0
	v_and_b32_e32 v23, 0xffff0000, v23
	v_pk_mul_f32 v[26:27], v[28:29], v[58:59] op_sel_hi:[1,0]
	v_add_f32_e32 v0, 1.0, v0
	v_rcp_f32_e32 v35, v0
	v_mul_f32_e32 v0, 0xbfb8aa3b, v22
	v_exp_f32_e32 v0, v0
	v_pk_mul_f32 v[20:21], v[26:27], v[20:21]
	v_pk_mul_f32 v[24:25], v[34:35], v[24:25]
	v_add_f32_e32 v0, 1.0, v0
	v_pk_mul_f32 v[18:19], v[18:19], v[24:25]
	v_rcp_f32_e32 v24, v0
	v_mul_f32_e32 v0, 0xbfb8aa3b, v23
	v_exp_f32_e32 v0, v0
	v_cvt_pk_bf16_f32 v18, v18, v19
	v_add_f32_e32 v0, 1.0, v0
	v_rcp_f32_e32 v25, v0
	s_nop 0
	v_pk_mul_f32 v[22:23], v[24:25], v[22:23]
	s_nop 0
	v_pk_mul_f32 v[20:21], v[20:21], v[22:23]
	s_nop 0
	v_cvt_pk_bf16_f32 v19, v20, v21
	global_load_dwordx4 v[22:25], v[64:65], off offset:352
	global_load_dwordx2 v[20:21], v[62:63], off offset:2224
	s_waitcnt vmcnt(0)
	v_pk_mul_f32 v[24:25], v[32:33], v[24:25]
	v_lshlrev_b32_e32 v26, 16, v21
	v_mul_f32_e32 v0, 0xbfb8aa3b, v26
	v_exp_f32_e32 v0, v0
	v_and_b32_e32 v27, 0xffff0000, v21
	v_add_f32_e32 v0, 1.0, v0
	v_rcp_f32_e32 v28, v0
	v_mul_f32_e32 v0, 0xbfb8aa3b, v27
	v_exp_f32_e32 v0, v0
	s_nop 0
	v_add_f32_e32 v0, 1.0, v0
	v_rcp_f32_e32 v29, v0
	s_nop 0
	v_pk_mul_f32 v[26:27], v[28:29], v[26:27]
	s_nop 0
	v_pk_mul_f32 v[24:25], v[24:25], v[26:27]
	v_pk_mul_f32 v[28:29], v[30:31], v[58:59] op_sel_hi:[1,0]
	v_cvt_pk_bf16_f32 v21, v24, v25
	v_lshlrev_b32_e32 v24, 16, v20
	v_mul_f32_e32 v0, 0xbfb8aa3b, v24
	v_exp_f32_e32 v0, v0
	v_and_b32_e32 v25, 0xffff0000, v20
	v_pk_mul_f32 v[22:23], v[28:29], v[22:23]
	v_permlane32_swap_b32_e32 v19, v21
	v_add_f32_e32 v0, 1.0, v0
	v_rcp_f32_e32 v26, v0
	v_mul_f32_e32 v0, 0xbfb8aa3b, v25
	v_exp_f32_e32 v0, v0
	s_nop 0
	v_add_f32_e32 v0, 1.0, v0
	v_rcp_f32_e32 v27, v0
	s_nop 0
	v_pk_mul_f32 v[24:25], v[26:27], v[24:25]
	s_nop 0
	v_pk_mul_f32 v[22:23], v[22:23], v[24:25]
	s_nop 0
	v_cvt_pk_bf16_f32 v20, v22, v23
	s_nop 1
	v_permlane32_swap_b32_e32 v18, v20
	global_store_dwordx4 v[60:61], v[18:21], off offset:160 sc1
	global_load_dwordx2 v[22:23], v[62:63], off offset:2240
	s_nop 0
	global_load_dwordx4 v[18:21], v[64:65], off offset:384
	s_waitcnt vmcnt(0)
	v_lshlrev_b32_e32 v24, 16, v22
	v_mul_f32_e32 v0, 0xbfb8aa3b, v24
	v_exp_f32_e32 v0, v0
	v_and_b32_e32 v25, 0xffff0000, v22
	v_pk_mul_f32 v[2:3], v[2:3], v[18:19]
	v_pk_mul_f32 v[4:5], v[4:5], v[20:21]
	v_add_f32_e32 v0, 1.0, v0
	v_rcp_f32_e32 v26, v0
	v_mul_f32_e32 v0, 0xbfb8aa3b, v25
	v_exp_f32_e32 v0, v0
	s_nop 0
	v_add_f32_e32 v0, 1.0, v0
	v_rcp_f32_e32 v27, v0
	s_nop 0
	v_pk_mul_f32 v[18:19], v[26:27], v[24:25]
	s_nop 0
	v_pk_mul_f32 v[2:3], v[2:3], v[18:19]
	v_lshlrev_b32_e32 v18, 16, v23
	v_mul_f32_e32 v0, 0xbfb8aa3b, v18
	v_exp_f32_e32 v0, v0
	v_and_b32_e32 v19, 0xffff0000, v23
	v_cvt_pk_bf16_f32 v2, v2, v3
	v_add_f32_e32 v0, 1.0, v0
	v_rcp_f32_e32 v22, v0
	v_mul_f32_e32 v0, 0xbfb8aa3b, v19
	v_exp_f32_e32 v0, v0
	s_nop 0
	v_add_f32_e32 v0, 1.0, v0
	v_rcp_f32_e32 v23, v0
	s_nop 0
	v_pk_mul_f32 v[18:19], v[22:23], v[18:19]
	s_nop 0
	v_pk_mul_f32 v[4:5], v[4:5], v[18:19]
	s_nop 0
	v_cvt_pk_bf16_f32 v3, v4, v5
	global_load_dwordx4 v[18:21], v[64:65], off offset:416
	global_load_dwordx2 v[4:5], v[62:63], off offset:2256
	s_waitcnt vmcnt(0)
	v_pk_mul_f32 v[8:9], v[8:9], v[20:21]
	v_lshlrev_b32_e32 v22, 16, v5
	v_mul_f32_e32 v0, 0xbfb8aa3b, v22
	v_exp_f32_e32 v0, v0
	v_and_b32_e32 v23, 0xffff0000, v5
	v_pk_mul_f32 v[6:7], v[6:7], v[18:19]
	v_add_f32_e32 v0, 1.0, v0
	v_rcp_f32_e32 v24, v0
	v_mul_f32_e32 v0, 0xbfb8aa3b, v23
	v_exp_f32_e32 v0, v0
	s_nop 0
	v_add_f32_e32 v0, 1.0, v0
	v_rcp_f32_e32 v25, v0
	s_nop 0
	v_pk_mul_f32 v[20:21], v[24:25], v[22:23]
	s_nop 0
	v_pk_mul_f32 v[8:9], v[8:9], v[20:21]
	s_nop 0
	v_cvt_pk_bf16_f32 v5, v8, v9
	v_lshlrev_b32_e32 v8, 16, v4
	v_mul_f32_e32 v0, 0xbfb8aa3b, v8
	v_exp_f32_e32 v0, v0
	v_and_b32_e32 v9, 0xffff0000, v4
	v_permlane32_swap_b32_e32 v3, v5
	v_add_f32_e32 v0, 1.0, v0
	v_rcp_f32_e32 v20, v0
	v_mul_f32_e32 v0, 0xbfb8aa3b, v9
	v_exp_f32_e32 v0, v0
	s_nop 0
	v_add_f32_e32 v0, 1.0, v0
	v_rcp_f32_e32 v21, v0
	s_nop 0
	v_pk_mul_f32 v[8:9], v[20:21], v[8:9]
	s_nop 0
	v_pk_mul_f32 v[6:7], v[6:7], v[8:9]
	s_nop 0
	v_cvt_pk_bf16_f32 v4, v6, v7
	s_nop 1
	v_permlane32_swap_b32_e32 v2, v4
	global_store_dwordx4 v[60:61], v[2:5], off offset:192 sc1
	global_load_dwordx2 v[6:7], v[62:63], off offset:2272
	s_nop 0
	global_load_dwordx4 v[2:5], v[64:65], off offset:448
	s_waitcnt vmcnt(0)
	v_lshlrev_b32_e32 v8, 16, v6
	v_mul_f32_e32 v0, 0xbfb8aa3b, v8
	v_exp_f32_e32 v0, v0
	v_and_b32_e32 v9, 0xffff0000, v6
	v_lshlrev_b32_e32 v6, 16, v7
	v_pk_mul_f32 v[2:3], v[10:11], v[2:3]
	v_add_f32_e32 v0, 1.0, v0
	v_rcp_f32_e32 v18, v0
	v_mul_f32_e32 v0, 0xbfb8aa3b, v9
	v_exp_f32_e32 v0, v0
	v_and_b32_e32 v7, 0xffff0000, v7
	v_pk_mul_f32 v[10:11], v[12:13], v[58:59] op_sel_hi:[1,0]
	v_add_f32_e32 v0, 1.0, v0
	v_rcp_f32_e32 v19, v0
	v_mul_f32_e32 v0, 0xbfb8aa3b, v6
	v_exp_f32_e32 v0, v0
	v_pk_mul_f32 v[4:5], v[10:11], v[4:5]
	v_pk_mul_f32 v[8:9], v[18:19], v[8:9]
	v_add_f32_e32 v0, 1.0, v0
	v_pk_mul_f32 v[2:3], v[2:3], v[8:9]
	v_rcp_f32_e32 v8, v0
	v_mul_f32_e32 v0, 0xbfb8aa3b, v7
	v_exp_f32_e32 v0, v0
	v_cvt_pk_bf16_f32 v2, v2, v3
	v_add_f32_e32 v0, 1.0, v0
	v_rcp_f32_e32 v9, v0
	s_nop 0
	v_pk_mul_f32 v[6:7], v[8:9], v[6:7]
	s_nop 0
	v_pk_mul_f32 v[4:5], v[4:5], v[6:7]
	s_nop 0
	v_cvt_pk_bf16_f32 v3, v4, v5
	global_load_dwordx4 v[6:9], v[64:65], off offset:480
	global_load_dwordx2 v[4:5], v[62:63], off offset:2288
	s_waitcnt vmcnt(0)
	v_pk_mul_f32 v[8:9], v[16:17], v[8:9]
	v_lshlrev_b32_e32 v10, 16, v5
	v_mul_f32_e32 v0, 0xbfb8aa3b, v10
	v_exp_f32_e32 v0, v0
	v_and_b32_e32 v11, 0xffff0000, v5
	v_add_f32_e32 v0, 1.0, v0
	v_rcp_f32_e32 v12, v0
	v_mul_f32_e32 v0, 0xbfb8aa3b, v11
	v_exp_f32_e32 v0, v0
	s_nop 0
	v_add_f32_e32 v0, 1.0, v0
	v_rcp_f32_e32 v13, v0
	s_nop 0
	v_pk_mul_f32 v[10:11], v[12:13], v[10:11]
	s_nop 0
	v_pk_mul_f32 v[8:9], v[8:9], v[10:11]
	v_pk_mul_f32 v[12:13], v[14:15], v[58:59] op_sel_hi:[1,0]
	v_cvt_pk_bf16_f32 v5, v8, v9
	v_lshlrev_b32_e32 v8, 16, v4
	v_mul_f32_e32 v0, 0xbfb8aa3b, v8
	v_exp_f32_e32 v0, v0
	v_and_b32_e32 v9, 0xffff0000, v4
	v_pk_mul_f32 v[6:7], v[12:13], v[6:7]
	v_permlane32_swap_b32_e32 v3, v5
	v_add_f32_e32 v0, 1.0, v0
	v_rcp_f32_e32 v10, v0
	v_mul_f32_e32 v0, 0xbfb8aa3b, v9
	v_exp_f32_e32 v0, v0
	s_nop 0
	v_add_f32_e32 v0, 1.0, v0
	v_rcp_f32_e32 v11, v0
	s_nop 0
	v_pk_mul_f32 v[8:9], v[10:11], v[8:9]
	s_nop 0
	v_pk_mul_f32 v[6:7], v[6:7], v[8:9]
	s_nop 0
	v_cvt_pk_bf16_f32 v4, v6, v7
	s_nop 1
	v_permlane32_swap_b32_e32 v2, v4
	global_store_dwordx4 v[60:61], v[2:5], off offset:224 sc1

; __device__ __forceinline__ unsigned cvtpk(float lo, float hi) { f32x2_t v = {lo, hi}; bf16x2_t b = __builtin_convertvector(v, bf16x2_t); return __builtin_bit_cast(unsigned, b); }
; __device__ __forceinline__ float bf_lo(unsigned w) { return __uint_as_float(w << 16); }
; __device__ __forceinline__ float bf_hi(unsigned w) { return __uint_as_float(w & 0xffff0000u); }
; __device__ __forceinline__ float half_sum(float m) { auto rr = __builtin_amdgcn_permlane32_swap(__float_as_uint(m), __float_as_uint(m), false, false); return __uint_as_float(rr[0]) + __uint_as_float(rr[1]); }
; __device__ __forceinline__ float silu_f(float x) { return x * __builtin_amdgcn_rcpf(1.f + __expf(-x)); }
; __device__ __forceinline__ void swa_unit(int b, int kvh, int qb, const bf16* U, const bf16* VTb, bf16* Y, const float* sinks, const float* qgain, const int* pos, unsigned char* lds, int wid, int lane) {
;     ...
;         const float inv = 1.0f / half_sum(l);
;         const bf16* gbr = U + (rowbase + tq) * EU + C_GB + qh * 64;
;         bf16* yr = Y + (rowbase + tq) * D + 512 + qh * 64; u32x2 wprev = {0u, 0u};
; #pragma unroll
;         for (int db = 0; db < 2; ++db)
; #pragma unroll
;             for (int g4 = 0; g4 < 4; ++g4) {
;                 const int e = 32 * db + 8 * g4 + 4 * hi;
;                 const u32x2 gw = *(const u32x2*)(gbr + e);
;                 const float y0 = o[db][4 * g4 + 0] * inv * silu_f(bf_lo(gw.x)), y1 = o[db][4 * g4 + 1] * inv * silu_f(bf_hi(gw.x));
;                 const float y2 = o[db][4 * g4 + 2] * inv * silu_f(bf_lo(gw.y)), y3 = o[db][4 * g4 + 3] * inv * silu_f(bf_hi(gw.y));
;                 u32x2 w; w.x = cvtpk(y0, y1); w.y = cvtpk(y2, y3);
;                 if ((g4 & 1) == 0) wprev = w; else store_pair16(yr + 32 * db + 16 * (g4 >> 1) + 8 * hi, wprev, w);
;             }
.LBB0_456:
	s_lshl_b32 s0, s14, 6
	s_lshl_b32 s2, s0, 1
	v_lshl_add_u64 v[4:5], v[114:115], 0, s[2:3]
	s_waitcnt vmcnt(0)
	v_mov_b32_e32 v0, v3
	s_nop 1
	v_permlane32_swap_b32_e32 v3, v0
	v_add_f32_e32 v0, v3, v0
	v_div_scale_f32 v10, s[0:1], v0, v0, 1.0
	v_rcp_f32_e32 v11, v10
	v_div_scale_f32 v12, vcc, 1.0, v0, 1.0
	v_lshl_add_u64 v[2:3], v[112:113], 0, s[2:3]
	v_fma_f32 v13, -v10, v11, 1.0
	v_fmac_f32_e32 v11, v13, v11
	v_mul_f32_e32 v13, v12, v11
	v_fma_f32 v14, -v10, v13, v12
	v_fmac_f32_e32 v13, v14, v11
	v_fma_f32 v10, -v10, v13, v12
	v_div_fmas_f32 v10, v10, v11, v13
	v_div_fixup_f32 v0, v10, v0, 1.0
	v_pk_mul_f32 v[10:11], v[32:33], v[0:1] op_sel_hi:[1,0]
	v_pk_mul_f32 v[12:13], v[34:35], v[0:1] op_sel_hi:[1,0]
	v_pk_mul_f32 v[14:15], v[38:39], v[0:1] op_sel_hi:[1,0]
	v_pk_mul_f32 v[32:33], v[36:37], v[0:1] op_sel_hi:[1,0]
	s_add_i32 s24, s24, 1
	s_cmp_eq_u32 s24, 4
	v_mov_b64_e32 v[6:7], v[144:145]
	v_mov_b64_e32 v[8:9], v[146:147]
	v_lshlrev_b32_e32 v34, 16, v6
	v_and_b32_e32 v35, 0xffff0000, v6
	v_lshlrev_b32_e32 v6, 16, v7
	v_and_b32_e32 v7, 0xffff0000, v7
	v_lshlrev_b32_e32 v36, 16, v9
	v_and_b32_e32 v37, 0xffff0000, v9
	v_lshlrev_b32_e32 v38, 16, v8
	v_and_b32_e32 v39, 0xffff0000, v8
	v_mul_f32_e32 v8, 0xbfb8aa3b, v34
	v_mul_f32_e32 v9, 0xbfb8aa3b, v35
	v_mul_f32_e32 v48, 0xbfb8aa3b, v6
	v_mul_f32_e32 v49, 0xbfb8aa3b, v7
	v_mul_f32_e32 v50, 0xbfb8aa3b, v36
	v_mul_f32_e32 v51, 0xbfb8aa3b, v37
	v_mul_f32_e32 v52, 0xbfb8aa3b, v38
	v_mul_f32_e32 v53, 0xbfb8aa3b, v39
	v_exp_f32_e32 v8, v8
	v_exp_f32_e32 v9, v9
	v_exp_f32_e32 v48, v48
	v_exp_f32_e32 v49, v49
	v_exp_f32_e32 v50, v50
	v_exp_f32_e32 v51, v51
	v_exp_f32_e32 v52, v52
	v_exp_f32_e32 v53, v53
	v_add_f32_e32 v8, 1.0, v8
	v_add_f32_e32 v9, 1.0, v9
	v_add_f32_e32 v48, 1.0, v48
	v_add_f32_e32 v49, 1.0, v49
	v_add_f32_e32 v50, 1.0, v50
	v_add_f32_e32 v51, 1.0, v51
	v_add_f32_e32 v52, 1.0, v52
	v_add_f32_e32 v53, 1.0, v53
	v_rcp_f32_e32 v8, v8
	v_rcp_f32_e32 v9, v9
	v_rcp_f32_e32 v48, v48
	v_rcp_f32_e32 v49, v49
	v_rcp_f32_e32 v50, v50
	v_rcp_f32_e32 v51, v51
	v_rcp_f32_e32 v52, v52
	v_rcp_f32_e32 v53, v53
	v_pk_mul_f32 v[8:9], v[8:9], v[34:35]
	v_pk_mul_f32 v[6:7], v[48:49], v[6:7]
	v_pk_mul_f32 v[34:35], v[50:51], v[36:37]
	v_pk_mul_f32 v[36:37], v[52:53], v[38:39]
	v_pk_mul_f32 v[8:9], v[10:11], v[8:9]
	v_pk_mul_f32 v[10:11], v[12:13], v[6:7]
	v_pk_mul_f32 v[12:13], v[14:15], v[34:35]
	v_pk_mul_f32 v[14:15], v[32:33], v[36:37]
	v_cvt_pk_bf16_f32 v6, v8, v9
	v_cvt_pk_bf16_f32 v7, v10, v11
	v_cvt_pk_bf16_f32 v9, v12, v13
	v_cvt_pk_bf16_f32 v8, v14, v15
	s_nop 1
	v_permlane32_swap_b32_e32 v6, v8
	v_permlane32_swap_b32_e32 v7, v9
	global_store_dwordx4 v[2:3], v[6:9], off offset:1024 sc1
	s_nop 1
	v_mov_b64_e32 v[6:7], v[148:149]
	v_mov_b64_e32 v[8:9], v[150:151]
	v_pk_mul_f32 v[10:11], v[40:41], v[0:1] op_sel_hi:[1,0]
	v_pk_mul_f32 v[12:13], v[42:43], v[0:1] op_sel_hi:[1,0]
	v_pk_mul_f32 v[32:33], v[44:45], v[0:1] op_sel_hi:[1,0]
	v_pk_mul_f32 v[14:15], v[46:47], v[0:1] op_sel_hi:[1,0]
	v_lshlrev_b32_e32 v34, 16, v6
	v_and_b32_e32 v35, 0xffff0000, v6
	v_lshlrev_b32_e32 v6, 16, v7
	v_and_b32_e32 v7, 0xffff0000, v7
	v_lshlrev_b32_e32 v36, 16, v9
	v_and_b32_e32 v37, 0xffff0000, v9
	v_lshlrev_b32_e32 v38, 16, v8
	v_and_b32_e32 v39, 0xffff0000, v8
	v_mul_f32_e32 v8, 0xbfb8aa3b, v34
	v_mul_f32_e32 v9, 0xbfb8aa3b, v35
	v_mul_f32_e32 v40, 0xbfb8aa3b, v6
	v_mul_f32_e32 v41, 0xbfb8aa3b, v7
	v_mul_f32_e32 v42, 0xbfb8aa3b, v36
	v_mul_f32_e32 v43, 0xbfb8aa3b, v37
	v_mul_f32_e32 v44, 0xbfb8aa3b, v38
	v_mul_f32_e32 v45, 0xbfb8aa3b, v39
	v_exp_f32_e32 v8, v8
	v_exp_f32_e32 v9, v9
	v_exp_f32_e32 v40, v40
	v_exp_f32_e32 v41, v41
	v_exp_f32_e32 v42, v42
	v_exp_f32_e32 v43, v43
	v_exp_f32_e32 v44, v44
	v_exp_f32_e32 v45, v45
	v_add_f32_e32 v8, 1.0, v8
	v_add_f32_e32 v9, 1.0, v9
	v_add_f32_e32 v40, 1.0, v40
	v_add_f32_e32 v41, 1.0, v41
	v_add_f32_e32 v42, 1.0, v42
	v_add_f32_e32 v43, 1.0, v43
	v_add_f32_e32 v44, 1.0, v44
	v_add_f32_e32 v45, 1.0, v45
	v_rcp_f32_e32 v8, v8
	v_rcp_f32_e32 v9, v9
	v_rcp_f32_e32 v40, v40
	v_rcp_f32_e32 v41, v41
	v_rcp_f32_e32 v42, v42
	v_rcp_f32_e32 v43, v43
	v_rcp_f32_e32 v44, v44
	v_rcp_f32_e32 v45, v45
	v_pk_mul_f32 v[8:9], v[8:9], v[34:35]
	v_pk_mul_f32 v[6:7], v[40:41], v[6:7]
	v_pk_mul_f32 v[34:35], v[42:43], v[36:37]
	v_pk_mul_f32 v[36:37], v[44:45], v[38:39]
	v_pk_mul_f32 v[8:9], v[10:11], v[8:9]
	v_pk_mul_f32 v[10:11], v[12:13], v[6:7]
	v_pk_mul_f32 v[12:13], v[14:15], v[34:35]
; __device__ __forceinline__ unsigned cvtpk(float lo, float hi) { f32x2_t v = {lo, hi}; bf16x2_t b = __builtin_convertvector(v, bf16x2_t); return __builtin_bit_cast(unsigned, b); }
; __device__ __forceinline__ float bf_lo(unsigned w) { return __uint_as_float(w << 16); }
; __device__ __forceinline__ float bf_hi(unsigned w) { return __uint_as_float(w & 0xffff0000u); }
; __device__ __forceinline__ float half_sum(float m) { auto rr = __builtin_amdgcn_permlane32_swap(__float_as_uint(m), __float_as_uint(m), false, false); return __uint_as_float(rr[0]) + __uint_as_float(rr[1]); }
; __device__ __forceinline__ float silu_f(float x) { return x * __builtin_amdgcn_rcpf(1.f + __expf(-x)); }
; __device__ __forceinline__ void swa_unit(int b, int kvh, int qb, const bf16* U, const bf16* VTb, bf16* Y, const float* sinks, const float* qgain, const int* pos, unsigned char* lds, int wid, int lane) {
;     ...
;         const float inv = 1.0f / half_sum(l);
;         const bf16* gbr = U + (rowbase + tq) * EU + C_GB + qh * 64;
;         bf16* yr = Y + (rowbase + tq) * D + 512 + qh * 64; u32x2 wprev = {0u, 0u};
; #pragma unroll
;         for (int db = 0; db < 2; ++db)
; #pragma unroll
;             for (int g4 = 0; g4 < 4; ++g4) {
;                 const int e = 32 * db + 8 * g4 + 4 * hi;
;                 const u32x2 gw = *(const u32x2*)(gbr + e);
;                 const float y0 = o[db][4 * g4 + 0] * inv * silu_f(bf_lo(gw.x)), y1 = o[db][4 * g4 + 1] * inv * silu_f(bf_hi(gw.x));
;                 const float y2 = o[db][4 * g4 + 2] * inv * silu_f(bf_lo(gw.y)), y3 = o[db][4 * g4 + 3] * inv * silu_f(bf_hi(gw.y));
;                 u32x2 w; w.x = cvtpk(y0, y1); w.y = cvtpk(y2, y3);
;                 if ((g4 & 1) == 0) wprev = w; else store_pair16(yr + 32 * db + 16 * (g4 >> 1) + 8 * hi, wprev, w);
;             }
	v_pk_mul_f32 v[14:15], v[32:33], v[36:37]
	v_cvt_pk_bf16_f32 v6, v8, v9
	v_cvt_pk_bf16_f32 v7, v10, v11
	v_cvt_pk_bf16_f32 v9, v12, v13
	v_cvt_pk_bf16_f32 v8, v14, v15
	s_nop 1
	v_permlane32_swap_b32_e32 v6, v8
	v_permlane32_swap_b32_e32 v7, v9
	global_store_dwordx4 v[2:3], v[6:9], off offset:1056 sc1
	s_nop 1
	v_mov_b64_e32 v[6:7], v[152:153]
	v_mov_b64_e32 v[8:9], v[154:155]
	v_pk_mul_f32 v[10:11], v[16:17], v[0:1] op_sel_hi:[1,0]
	v_pk_mul_f32 v[12:13], v[18:19], v[0:1] op_sel_hi:[1,0]
	v_pk_mul_f32 v[14:15], v[22:23], v[0:1] op_sel_hi:[1,0]
	v_pk_mul_f32 v[16:17], v[20:21], v[0:1] op_sel_hi:[1,0]
	v_lshlrev_b32_e32 v18, 16, v6
	v_and_b32_e32 v19, 0xffff0000, v6
	v_lshlrev_b32_e32 v6, 16, v7
	v_and_b32_e32 v7, 0xffff0000, v7
	v_lshlrev_b32_e32 v20, 16, v9
	v_and_b32_e32 v21, 0xffff0000, v9
	v_lshlrev_b32_e32 v22, 16, v8
	v_and_b32_e32 v23, 0xffff0000, v8
	v_mul_f32_e32 v8, 0xbfb8aa3b, v18
	v_mul_f32_e32 v9, 0xbfb8aa3b, v19
	v_mul_f32_e32 v32, 0xbfb8aa3b, v6
	v_mul_f32_e32 v33, 0xbfb8aa3b, v7
	v_mul_f32_e32 v34, 0xbfb8aa3b, v20
	v_mul_f32_e32 v35, 0xbfb8aa3b, v21
	v_mul_f32_e32 v36, 0xbfb8aa3b, v22
	v_mul_f32_e32 v37, 0xbfb8aa3b, v23
	v_exp_f32_e32 v8, v8
	v_exp_f32_e32 v9, v9
	v_exp_f32_e32 v32, v32
	v_exp_f32_e32 v33, v33
	v_exp_f32_e32 v34, v34
	v_exp_f32_e32 v35, v35
	v_exp_f32_e32 v36, v36
	v_exp_f32_e32 v37, v37
	v_add_f32_e32 v8, 1.0, v8
	v_add_f32_e32 v9, 1.0, v9
	v_add_f32_e32 v32, 1.0, v32
	v_add_f32_e32 v33, 1.0, v33
	v_add_f32_e32 v34, 1.0, v34
	v_add_f32_e32 v35, 1.0, v35
	v_add_f32_e32 v36, 1.0, v36
	v_add_f32_e32 v37, 1.0, v37
	v_rcp_f32_e32 v8, v8
	v_rcp_f32_e32 v9, v9
	v_rcp_f32_e32 v32, v32
	v_rcp_f32_e32 v33, v33
	v_rcp_f32_e32 v34, v34
	v_rcp_f32_e32 v35, v35
	v_rcp_f32_e32 v36, v36
	v_rcp_f32_e32 v37, v37
	v_pk_mul_f32 v[8:9], v[8:9], v[18:19]
	v_pk_mul_f32 v[6:7], v[32:33], v[6:7]
	v_pk_mul_f32 v[18:19], v[34:35], v[20:21]
	v_pk_mul_f32 v[20:21], v[36:37], v[22:23]
	v_pk_mul_f32 v[8:9], v[10:11], v[8:9]
	v_pk_mul_f32 v[10:11], v[12:13], v[6:7]
	v_pk_mul_f32 v[12:13], v[14:15], v[18:19]
	v_pk_mul_f32 v[14:15], v[16:17], v[20:21]
	v_cvt_pk_bf16_f32 v6, v8, v9
	v_cvt_pk_bf16_f32 v7, v10, v11
	v_cvt_pk_bf16_f32 v9, v12, v13
	v_cvt_pk_bf16_f32 v8, v14, v15
	s_nop 1
	v_permlane32_swap_b32_e32 v6, v8
	v_permlane32_swap_b32_e32 v7, v9
	global_store_dwordx4 v[2:3], v[6:9], off offset:1088 sc1
	s_nop 1
	v_mov_b64_e32 v[6:7], v[156:157]
	v_mov_b64_e32 v[4:5], v[158:159]
	v_pk_mul_f32 v[8:9], v[24:25], v[0:1] op_sel_hi:[1,0]
	v_pk_mul_f32 v[10:11], v[26:27], v[0:1] op_sel_hi:[1,0]
	v_pk_mul_f32 v[12:13], v[30:31], v[0:1] op_sel_hi:[1,0]
	v_pk_mul_f32 v[14:15], v[28:29], v[0:1] op_sel_hi:[1,0]
	v_lshlrev_b32_e32 v16, 16, v6
	v_and_b32_e32 v17, 0xffff0000, v6
	v_lshlrev_b32_e32 v6, 16, v7
	v_and_b32_e32 v7, 0xffff0000, v7
	v_lshlrev_b32_e32 v18, 16, v5
	v_and_b32_e32 v19, 0xffff0000, v5
	v_lshlrev_b32_e32 v20, 16, v4
	v_and_b32_e32 v21, 0xffff0000, v4
	v_mul_f32_e32 v0, 0xbfb8aa3b, v16
	v_mul_f32_e32 v4, 0xbfb8aa3b, v17
	v_mul_f32_e32 v5, 0xbfb8aa3b, v6
	v_mul_f32_e32 v22, 0xbfb8aa3b, v7
	v_mul_f32_e32 v23, 0xbfb8aa3b, v18
	v_mul_f32_e32 v24, 0xbfb8aa3b, v19
	v_mul_f32_e32 v25, 0xbfb8aa3b, v20
	v_mul_f32_e32 v26, 0xbfb8aa3b, v21
	v_exp_f32_e32 v0, v0
	v_exp_f32_e32 v4, v4
	v_exp_f32_e32 v5, v5
	v_exp_f32_e32 v22, v22
	v_exp_f32_e32 v23, v23
	v_exp_f32_e32 v24, v24
	v_exp_f32_e32 v25, v25
	v_exp_f32_e32 v26, v26
	v_add_f32_e32 v0, 1.0, v0
	v_add_f32_e32 v27, 1.0, v4
	v_add_f32_e32 v28, 1.0, v5
	v_add_f32_e32 v29, 1.0, v22
	v_add_f32_e32 v30, 1.0, v23
	v_add_f32_e32 v31, 1.0, v24
	v_add_f32_e32 v32, 1.0, v25
	v_add_f32_e32 v33, 1.0, v26
	v_rcp_f32_e32 v4, v0
	v_rcp_f32_e32 v5, v27
	v_rcp_f32_e32 v22, v28
	v_rcp_f32_e32 v23, v29
	v_rcp_f32_e32 v24, v30
	v_rcp_f32_e32 v25, v31
	v_rcp_f32_e32 v26, v32
	v_rcp_f32_e32 v27, v33
	v_pk_mul_f32 v[4:5], v[4:5], v[16:17]
	v_pk_mul_f32 v[6:7], v[22:23], v[6:7]
	v_pk_mul_f32 v[16:17], v[24:25], v[18:19]
	v_pk_mul_f32 v[18:19], v[26:27], v[20:21]
	v_pk_mul_f32 v[4:5], v[8:9], v[4:5]
	v_pk_mul_f32 v[6:7], v[10:11], v[6:7]
	v_pk_mul_f32 v[8:9], v[12:13], v[16:17]
	v_pk_mul_f32 v[10:11], v[14:15], v[18:19]
	v_cvt_pk_bf16_f32 v4, v4, v5
	v_cvt_pk_bf16_f32 v5, v6, v7
	v_cvt_pk_bf16_f32 v7, v8, v9
	v_cvt_pk_bf16_f32 v6, v10, v11
	s_nop 1
	v_permlane32_swap_b32_e32 v4, v6
	v_permlane32_swap_b32_e32 v5, v7
	global_store_dwordx4 v[2:3], v[4:7], off offset:1120 sc1
	s_cbranch_scc1 .LBB0_451

; __device__ __forceinline__ unsigned cvtpk(float lo, float hi) { f32x2_t v = {lo, hi}; bf16x2_t b = __builtin_convertvector(v, bf16x2_t); return __builtin_bit_cast(unsigned, b); }
; __device__ __forceinline__ float bf_lo(unsigned w) { return __uint_as_float(w << 16); }
; __device__ __forceinline__ float bf_hi(unsigned w) { return __uint_as_float(w & 0xffff0000u); }
; __device__ __forceinline__ float silu_f(float x) { return x * __builtin_amdgcn_rcpf(1.f + __expf(-x)); }
; __device__ __forceinline__ int lane_now() { int l; asm volatile("v_mbcnt_lo_u32_b32 %0, -1, 0\n\tv_mbcnt_hi_u32_b32 %0, -1, %0" : "=v"(l)); return l; }
; __device__ __forceinline__ void sb_unit(int b, int h, int qb, const bf16* U, const bf16* VT, bf16* Y, unsigned char* lds, int wid, int lane, int& res_lo, int& res_hi) {
;     ...
;     const int lane_e = lane_now(); const int hi_e = lane_e >> 5, tq_e = t0 + (lane_e & 31);
;     bf16* yr = Y + (rowbase + tq_e) * D + h * 64; u32x2 wprev = {0u, 0u};
; #pragma unroll
;     for (int db = 0; db < 2; ++db)
; #pragma unroll
;         for (int g4 = 0; g4 < 4; ++g4) {
;             const int e = 32 * db + 8 * g4 + 4 * hi_e;
;             const u32x2 gw = gwv[db][g4];
;             const float y0 = o[db][4 * g4 + 0] * silu_f(bf_lo(gw.x)), y1 = o[db][4 * g4 + 1] * silu_f(bf_hi(gw.x));
;             const float y2 = o[db][4 * g4 + 2] * silu_f(bf_lo(gw.y)), y3 = o[db][4 * g4 + 3] * silu_f(bf_hi(gw.y));
;             u32x2 w; w.x = cvtpk(y0, y1); w.y = cvtpk(y2, y3);
;             if ((g4 & 1) == 0) wprev = w; else store_pair16(yr + 32 * db + 16 * (g4 >> 1) + 8 * hi_e, wprev, w);
;         }
.LBB0_721:
	s_barrier
	v_mbcnt_lo_u32_b32 v4, -1, 0
	v_mbcnt_hi_u32_b32 v4, -1, v4
	v_lshlrev_b32_e32 v6, 16, v136
	v_and_or_b32 v0, v4, 31, s86
	v_lshl_add_u64 v[2:3], s[74:75], 0, v[0:1]
	v_ashrrev_i32_e32 v0, 2, v4
	v_and_b32_e32 v4, -8, v0
	v_and_b32_e32 v7, 0xffff0000, v136
	v_mul_f32_e32 v0, 0xbfb8aa3b, v6
	v_exp_f32_e32 v0, v0
	v_mul_f32_e32 v5, 0xbfb8aa3b, v7
	v_exp_f32_e32 v9, v5
	v_lshlrev_b32_e32 v10, 16, v137
	v_add_f32_e32 v0, 1.0, v0
	v_rcp_f32_e32 v8, v0
	v_add_f32_e32 v0, 1.0, v9
	v_and_b32_e32 v11, 0xffff0000, v137
	v_mul_f32_e32 v9, 0xbfb8aa3b, v10
	v_exp_f32_e32 v12, v9
	v_mul_f32_e32 v9, 0xbfb8aa3b, v11
	v_exp_f32_e32 v13, v9
	v_rcp_f32_e32 v9, v0
	v_add_f32_e32 v0, 1.0, v12
	v_lshlrev_b64 v[2:3], 11, v[2:3]
	v_rcp_f32_e32 v12, v0
	v_add_f32_e32 v0, 1.0, v13
	v_lshl_add_u64 v[2:3], s[76:77], 0, v[2:3]
	v_ashrrev_i32_e32 v5, 31, v4
	v_rcp_f32_e32 v13, v0
	v_lshl_add_u64 v[2:3], v[4:5], 1, v[2:3]
	v_pk_mul_f32 v[4:5], v[8:9], v[6:7]
	v_lshlrev_b32_e32 v8, 16, v135
	v_pk_mul_f32 v[4:5], v[4:5], v[32:33]
	v_and_b32_e32 v9, 0xffff0000, v135
	v_mul_f32_e32 v0, 0xbfb8aa3b, v8
	v_cvt_pk_bf16_f32 v4, v4, v5
	v_exp_f32_e32 v0, v0
	v_mul_f32_e32 v5, 0xbfb8aa3b, v9
	v_pk_mul_f32 v[6:7], v[12:13], v[10:11]
	v_exp_f32_e32 v10, v5
	v_pk_mul_f32 v[6:7], v[6:7], v[34:35]
	v_add_f32_e32 v0, 1.0, v0
	v_cvt_pk_bf16_f32 v5, v6, v7
	v_rcp_f32_e32 v6, v0
	v_add_f32_e32 v0, 1.0, v10
	v_lshlrev_b32_e32 v10, 16, v134
	v_and_b32_e32 v11, 0xffff0000, v134
	v_mul_f32_e32 v7, 0xbfb8aa3b, v10
	v_exp_f32_e32 v12, v7
	v_mul_f32_e32 v7, 0xbfb8aa3b, v11
	v_exp_f32_e32 v13, v7
	v_rcp_f32_e32 v7, v0
	v_add_f32_e32 v0, 1.0, v12
	v_rcp_f32_e32 v12, v0
	v_add_f32_e32 v0, 1.0, v13
	v_rcp_f32_e32 v13, v0
	v_pk_mul_f32 v[6:7], v[6:7], v[8:9]
	s_add_i32 s91, s91, 0xffff0000
	v_pk_mul_f32 v[6:7], v[6:7], v[38:39]
	v_pk_mul_f32 v[8:9], v[12:13], v[10:11]
	v_cvt_pk_bf16_f32 v7, v6, v7
	v_pk_mul_f32 v[8:9], v[8:9], v[36:37]
	v_lshlrev_b32_e32 v12, 16, v133
	v_cvt_pk_bf16_f32 v6, v8, v9
	v_lshlrev_b32_e32 v8, 16, v132
	v_and_b32_e32 v9, 0xffff0000, v132
	v_mul_f32_e32 v0, 0xbfb8aa3b, v8
	v_exp_f32_e32 v0, v0
	v_mul_f32_e32 v10, 0xbfb8aa3b, v9
	v_exp_f32_e32 v11, v10
	v_and_b32_e32 v13, 0xffff0000, v133
	v_add_f32_e32 v0, 1.0, v0
	v_rcp_f32_e32 v10, v0
	v_add_f32_e32 v0, 1.0, v11
	v_mul_f32_e32 v11, 0xbfb8aa3b, v12
	v_exp_f32_e32 v14, v11
	v_mul_f32_e32 v11, 0xbfb8aa3b, v13
	v_exp_f32_e32 v15, v11
	v_rcp_f32_e32 v11, v0
	v_permlane32_swap_b32_e32 v4, v6
	v_permlane32_swap_b32_e32 v5, v7
	v_add_f32_e32 v0, 1.0, v14
	v_rcp_f32_e32 v14, v0
	v_add_f32_e32 v0, 1.0, v15
	global_store_dwordx4 v[2:3], v[4:7], off sc1
	v_rcp_f32_e32 v15, v0
	s_add_u32 s78, s78, 0xfffffe00
	v_pk_mul_f32 v[4:5], v[10:11], v[8:9]
	v_lshlrev_b32_e32 v8, 16, v131
	v_pk_mul_f32 v[4:5], v[4:5], v[40:41]
	v_and_b32_e32 v9, 0xffff0000, v131
	v_mul_f32_e32 v0, 0xbfb8aa3b, v8
	v_cvt_pk_bf16_f32 v4, v4, v5
	v_exp_f32_e32 v0, v0
	v_mul_f32_e32 v5, 0xbfb8aa3b, v9
	v_exp_f32_e32 v10, v5
	v_pk_mul_f32 v[6:7], v[14:15], v[12:13]
	v_add_f32_e32 v0, 1.0, v0
	v_pk_mul_f32 v[6:7], v[6:7], v[42:43]
	v_and_b32_e32 v11, 0xffff0000, v130
	v_cvt_pk_bf16_f32 v5, v6, v7
	v_rcp_f32_e32 v6, v0
	v_add_f32_e32 v0, 1.0, v10
	v_lshlrev_b32_e32 v10, 16, v130
	v_mul_f32_e32 v7, 0xbfb8aa3b, v10
	v_exp_f32_e32 v12, v7
	v_mul_f32_e32 v7, 0xbfb8aa3b, v11
	v_exp_f32_e32 v13, v7
	v_rcp_f32_e32 v7, v0
	v_add_f32_e32 v0, 1.0, v12
	v_rcp_f32_e32 v12, v0
	v_add_f32_e32 v0, 1.0, v13
	v_rcp_f32_e32 v13, v0
	v_pk_mul_f32 v[6:7], v[6:7], v[8:9]
	s_addc_u32 s79, s79, -1
	v_pk_mul_f32 v[6:7], v[6:7], v[46:47]
	v_pk_mul_f32 v[8:9], v[12:13], v[10:11]
	v_cvt_pk_bf16_f32 v7, v6, v7
	v_pk_mul_f32 v[8:9], v[8:9], v[44:45]
	v_lshlrev_b32_e32 v12, 16, v129
	v_cvt_pk_bf16_f32 v6, v8, v9
; __device__ __forceinline__ unsigned cvtpk(float lo, float hi) { f32x2_t v = {lo, hi}; bf16x2_t b = __builtin_convertvector(v, bf16x2_t); return __builtin_bit_cast(unsigned, b); }
; __device__ __forceinline__ float bf_lo(unsigned w) { return __uint_as_float(w << 16); }
; __device__ __forceinline__ float bf_hi(unsigned w) { return __uint_as_float(w & 0xffff0000u); }
; __device__ __forceinline__ float silu_f(float x) { return x * __builtin_amdgcn_rcpf(1.f + __expf(-x)); }
; __device__ __forceinline__ int lane_now() { int l; asm volatile("v_mbcnt_lo_u32_b32 %0, -1, 0\n\tv_mbcnt_hi_u32_b32 %0, -1, %0" : "=v"(l)); return l; }
; __device__ __forceinline__ void sb_unit(int b, int h, int qb, const bf16* U, const bf16* VT, bf16* Y, unsigned char* lds, int wid, int lane, int& res_lo, int& res_hi) {
;     ...
;     const int lane_e = lane_now(); const int hi_e = lane_e >> 5, tq_e = t0 + (lane_e & 31);
;     bf16* yr = Y + (rowbase + tq_e) * D + h * 64; u32x2 wprev = {0u, 0u};
; #pragma unroll
;     for (int db = 0; db < 2; ++db)
; #pragma unroll
;         for (int g4 = 0; g4 < 4; ++g4) {
;             const int e = 32 * db + 8 * g4 + 4 * hi_e;
;             const u32x2 gw = gwv[db][g4];
;             const float y0 = o[db][4 * g4 + 0] * silu_f(bf_lo(gw.x)), y1 = o[db][4 * g4 + 1] * silu_f(bf_hi(gw.x));
;             const float y2 = o[db][4 * g4 + 2] * silu_f(bf_lo(gw.y)), y3 = o[db][4 * g4 + 3] * silu_f(bf_hi(gw.y));
;             u32x2 w; w.x = cvtpk(y0, y1); w.y = cvtpk(y2, y3);
;             if ((g4 & 1) == 0) wprev = w; else store_pair16(yr + 32 * db + 16 * (g4 >> 1) + 8 * hi_e, wprev, w);
;         }
	v_lshlrev_b32_e32 v8, 16, v128
	v_and_b32_e32 v9, 0xffff0000, v128
	v_mul_f32_e32 v0, 0xbfb8aa3b, v8
	v_exp_f32_e32 v0, v0
	v_mul_f32_e32 v10, 0xbfb8aa3b, v9
	v_exp_f32_e32 v11, v10
	v_and_b32_e32 v13, 0xffff0000, v129
	v_add_f32_e32 v0, 1.0, v0
	v_rcp_f32_e32 v10, v0
	v_add_f32_e32 v0, 1.0, v11
	v_mul_f32_e32 v11, 0xbfb8aa3b, v12
	v_exp_f32_e32 v14, v11
	v_mul_f32_e32 v11, 0xbfb8aa3b, v13
	v_exp_f32_e32 v15, v11
	v_rcp_f32_e32 v11, v0
	v_permlane32_swap_b32_e32 v4, v6
	v_permlane32_swap_b32_e32 v5, v7
	v_add_f32_e32 v0, 1.0, v14
	v_rcp_f32_e32 v14, v0
	v_add_f32_e32 v0, 1.0, v15
	global_store_dwordx4 v[2:3], v[4:7], off offset:32 sc1
	v_rcp_f32_e32 v15, v0
	s_add_u32 s80, s80, 0xffe80000
	v_pk_mul_f32 v[4:5], v[10:11], v[8:9]
	v_lshlrev_b32_e32 v8, 16, v127
	v_pk_mul_f32 v[4:5], v[4:5], v[16:17]
	v_and_b32_e32 v9, 0xffff0000, v127
	v_mul_f32_e32 v0, 0xbfb8aa3b, v8
	v_cvt_pk_bf16_f32 v4, v4, v5
	v_exp_f32_e32 v0, v0
	v_mul_f32_e32 v5, 0xbfb8aa3b, v9
	v_exp_f32_e32 v10, v5
	v_pk_mul_f32 v[6:7], v[14:15], v[12:13]
	v_add_f32_e32 v0, 1.0, v0
	v_pk_mul_f32 v[6:7], v[6:7], v[18:19]
	v_and_b32_e32 v11, 0xffff0000, v126
	v_cvt_pk_bf16_f32 v5, v6, v7
	v_rcp_f32_e32 v6, v0
	v_add_f32_e32 v0, 1.0, v10
	v_lshlrev_b32_e32 v10, 16, v126
	v_mul_f32_e32 v7, 0xbfb8aa3b, v10
	v_exp_f32_e32 v12, v7
	v_mul_f32_e32 v7, 0xbfb8aa3b, v11
	v_exp_f32_e32 v13, v7
	v_rcp_f32_e32 v7, v0
	v_add_f32_e32 v0, 1.0, v12
	v_rcp_f32_e32 v12, v0
	v_add_f32_e32 v0, 1.0, v13
	v_rcp_f32_e32 v13, v0
	v_pk_mul_f32 v[6:7], v[6:7], v[8:9]
	s_addc_u32 s81, s81, -1
	v_pk_mul_f32 v[6:7], v[6:7], v[22:23]
	v_pk_mul_f32 v[8:9], v[12:13], v[10:11]
	v_cvt_pk_bf16_f32 v7, v6, v7
	v_pk_mul_f32 v[8:9], v[8:9], v[20:21]
	v_lshlrev_b32_e32 v12, 16, v125
	v_cvt_pk_bf16_f32 v6, v8, v9
	v_lshlrev_b32_e32 v8, 16, v124
	v_and_b32_e32 v9, 0xffff0000, v124
	v_mul_f32_e32 v0, 0xbfb8aa3b, v8
	v_exp_f32_e32 v0, v0
	v_mul_f32_e32 v10, 0xbfb8aa3b, v9
	v_exp_f32_e32 v11, v10
	v_and_b32_e32 v13, 0xffff0000, v125
	v_add_f32_e32 v0, 1.0, v0
	v_rcp_f32_e32 v10, v0
	v_add_f32_e32 v0, 1.0, v11
	v_mul_f32_e32 v11, 0xbfb8aa3b, v12
	v_exp_f32_e32 v14, v11
	v_mul_f32_e32 v11, 0xbfb8aa3b, v13
	v_exp_f32_e32 v15, v11
	v_rcp_f32_e32 v11, v0
	v_permlane32_swap_b32_e32 v4, v6
	v_permlane32_swap_b32_e32 v5, v7
	v_add_f32_e32 v0, 1.0, v14
	v_rcp_f32_e32 v14, v0
	v_add_f32_e32 v0, 1.0, v15
	global_store_dwordx4 v[2:3], v[4:7], off offset:64 sc1
	v_rcp_f32_e32 v15, v0
	s_add_i32 s92, s92, -4
	v_pk_mul_f32 v[4:5], v[10:11], v[8:9]
	v_lshlrev_b32_e32 v8, 16, v123
	v_pk_mul_f32 v[4:5], v[4:5], v[24:25]
	v_and_b32_e32 v9, 0xffff0000, v123
	v_mul_f32_e32 v0, 0xbfb8aa3b, v8
	v_cvt_pk_bf16_f32 v4, v4, v5
	v_exp_f32_e32 v0, v0
	v_mul_f32_e32 v5, 0xbfb8aa3b, v9
	v_exp_f32_e32 v10, v5
	v_pk_mul_f32 v[6:7], v[14:15], v[12:13]
	v_add_f32_e32 v0, 1.0, v0
	v_pk_mul_f32 v[6:7], v[6:7], v[26:27]
	v_and_b32_e32 v11, 0xffff0000, v122
	v_cvt_pk_bf16_f32 v5, v6, v7
	v_rcp_f32_e32 v6, v0
	v_add_f32_e32 v0, 1.0, v10
	v_lshlrev_b32_e32 v10, 16, v122
	v_mul_f32_e32 v7, 0xbfb8aa3b, v10
	v_exp_f32_e32 v12, v7
	v_mul_f32_e32 v7, 0xbfb8aa3b, v11
	v_exp_f32_e32 v13, v7
	v_rcp_f32_e32 v7, v0
	v_add_f32_e32 v0, 1.0, v12
	v_rcp_f32_e32 v12, v0
	v_add_f32_e32 v0, 1.0, v13
	v_rcp_f32_e32 v13, v0
	v_pk_mul_f32 v[6:7], v[6:7], v[8:9]
	v_sub_co_u32_e64 v0, s[0:1], s85, 1
	v_pk_mul_f32 v[8:9], v[12:13], v[10:11]
	v_pk_mul_f32 v[6:7], v[6:7], v[30:31]
	v_pk_mul_f32 v[8:9], v[8:9], v[28:29]
	v_cvt_pk_bf16_f32 v7, v6, v7
	v_cvt_pk_bf16_f32 v6, v8, v9
	s_nop 1
	v_permlane32_swap_b32_e32 v4, v6
	v_permlane32_swap_b32_e32 v5, v7
	v_readfirstlane_b32 s85, v0
	s_add_i32 s96, s96, -4
	s_and_b64 vcc, exec, s[0:1]
	global_store_dwordx4 v[2:3], v[4:7], off offset:96 sc1
	s_cbranch_vccnz .LBB0_719
